# DPP forward substitution in column-major order (every DPP operand at least two slots old)
# speedup vs baseline: 1.0005x; 1.0005x over previous
; #define LAS __attribute__((address_space(3)))
; #define BAR_LDS() do { asm volatile("s_waitcnt lgkmcnt(0)" ::: "memory"); __builtin_amdgcn_s_barrier(); asm volatile("" ::: "memory"); } while (0)
; __device__ __forceinline__ void st_bf4(LAS bf16_t* p, f32x4 v) { u32x2 w; w.x = pk2(v.x, v.y); w.y = pk2(v.z, v.w); *(LAS u32x2*)p = w; }
; __device__ __forceinline__ void chunk_pre(const Params& p, LAS unsigned char* lds, int item, int next_item, int tid, int wave, int lane, h16 (&raw)[48]) {
;     ...
;     BAR_LDS();
;     const int a0 = 16 * (wave >> 1), ar = a0 + fr;
;     {
;         f32x4 acc[2];
; #pragma unroll
;         for (int which = 0; which < 4; ++which) {
;             acc[0] = (f32x4){0.f, 0.f, 0.f, 0.f}; acc[1] = acc[0];
;             mm64((which & 1) ? Kt : Bt, (which & 2) ? Rt : At, acc, wave, fr, fq);
; #pragma unroll
;             for (int nt = 0; nt < 2; ++nt) { const int s0 = 32 * (wave & 1) + 16 * nt + 4 * fq; f32x4 v = acc[nt];
; #pragma unroll
;                 for (int jj = 0; jj < 4; ++jj) { const bool keep = (which & 2) ? (s0 + jj <= ar) : (s0 + jj < ar); if (!keep) v[jj] = 0.f; }
;                 if (which == 0) *(LAS f32x4*)(Mab + ar * 64 + s0) = v;
;                 else st_bf4(((which == 1) ? Mak : (which == 2) ? Mrb : Mrk) + ar * MS + s0, v); }
;         }
;     }
;     BAR_LDS();
;     {
;         f32x4 acc[2]; acc[0] = (f32x4){0.f, 0.f, 0.f, 0.f}; acc[1] = acc[0];
;         mm64(Mak, VT, acc, wave, fr, fq);
; #pragma unroll
;         for (int nt = 0; nt < 2; ++nt) st_bf4(RH2T + ar * MS + 32 * (wave & 1) + 16 * nt + 4 * fq, acc[nt]);
;     }
;     for (int e = tid; e < 6 * 256; e += 512) { const int ub = e >> 8, i = (e >> 4) & 15, j = e & 15;
;         const int r = ub < 3 ? 0 : ub < 5 ? 1 : 2, c = ub < 3 ? ub + 1 : ub < 5 ? ub - 1 : 3; Tb[(16 * r + i) * MS + 16 * c + j] = 0; }
;     if (tid < 64) {
.LBB0_925:
	s_waitcnt lgkmcnt(0)
	s_barrier
	ds_read_b128 v[220:223], v91
	ds_read_b128 v[236:239], v161 offset:9216
	ds_read_b128 v[240:243], v161 offset:11520
	ds_read_b128 v[224:227], v91 offset:64
	ds_read_b128 v[184:187], v161 offset:9280
	ds_read_b128 v[188:191], v161 offset:11584
	ds_read_b128 v[192:195], v161 offset:18432
	ds_read_b128 v[196:199], v161 offset:20736
	ds_read_b128 v[200:203], v161 offset:18496
	ds_read_b128 v[206:209], v161 offset:20800
	ds_read_b128 v[228:231], v91 offset:27648
	ds_read_b128 v[232:235], v91 offset:27712
	s_or_b64 vcc, s[72:73], s[20:21]
	s_or_b64 s[80:81], s[76:77], s[24:25]
	s_waitcnt lgkmcnt(6)
	v_mfma_f32_16x16x32_bf16 v[8:11], v[236:239], v[220:223], 0
	v_mfma_f32_16x16x32_bf16 v[4:7], v[240:243], v[220:223], 0
	v_mfma_f32_16x16x32_bf16 v[8:11], v[184:187], v[224:227], v[8:11]
	v_mfma_f32_16x16x32_bf16 v[4:7], v[188:191], v[224:227], v[4:7]
	s_nop 7
	v_cndmask_b32_e64 v11, 0, v11, s[22:23]
	v_cndmask_b32_e64 v10, 0, v10, s[70:71]
	v_cndmask_b32_e64 v9, 0, v9, s[72:73]
	v_cndmask_b32_e32 v8, 0, v8, vcc
	v_cndmask_b32_e64 v7, 0, v7, s[26:27]
	v_cndmask_b32_e64 v6, 0, v6, s[74:75]
	v_cndmask_b32_e64 v5, 0, v5, s[76:77]
	v_cndmask_b32_e64 v4, 0, v4, s[80:81]
	ds_write_b128 v94, v[8:11]
	ds_write_b128 v94, v[4:7] offset:64
	s_waitcnt lgkmcnt(4)
	v_mfma_f32_16x16x32_bf16 v[8:11], v[192:195], v[220:223], 0
	v_mfma_f32_16x16x32_bf16 v[4:7], v[196:199], v[220:223], 0
	v_mfma_f32_16x16x32_bf16 v[8:11], v[200:203], v[224:227], v[8:11]
	v_mfma_f32_16x16x32_bf16 v[4:7], v[206:209], v[224:227], v[4:7]
	s_nop 7
	v_cndmask_b32_e64 v11, 0, v11, s[22:23]
	v_cndmask_b32_e64 v10, 0, v10, s[70:71]
	v_cndmask_b32_e64 v9, 0, v9, s[72:73]
	v_cndmask_b32_e32 v8, 0, v8, vcc
	v_cndmask_b32_e64 v7, 0, v7, s[26:27]
	v_cndmask_b32_e64 v6, 0, v6, s[74:75]
	v_cndmask_b32_e64 v5, 0, v5, s[76:77]
	v_cndmask_b32_e64 v4, 0, v4, s[80:81]
	v_cvt_pk_bf16_f32 v8, v8, v9
	v_cvt_pk_bf16_f32 v9, v10, v11
	v_cvt_pk_bf16_f32 v4, v4, v5
	v_cvt_pk_bf16_f32 v5, v6, v7
	v_add_u32_e32 v6, 0xf800, v95
	ds_write2_b64 v6, v[8:9], v[4:5] offset0:128 offset1:132
	s_waitcnt lgkmcnt(3)
	v_mfma_f32_16x16x32_bf16 v[8:11], v[236:239], v[228:231], 0
	v_mfma_f32_16x16x32_bf16 v[4:7], v[240:243], v[228:231], 0
	v_mfma_f32_16x16x32_bf16 v[8:11], v[184:187], v[232:235], v[8:11]
	v_mfma_f32_16x16x32_bf16 v[4:7], v[188:191], v[232:235], v[4:7]
	s_nop 7
	v_mov_b32_e32 v12, s9
	s_nop 3
	v_cndmask_b32_e64 v12, v8, v12, s[28:29]
	v_cndmask_b32_e64 v8, v12, v8, s[20:21]
	v_cndmask_b32_e64 v9, 0, v9, s[20:21]
	v_cndmask_b32_e64 v12, v10, 0, s[30:31]
	v_cvt_pk_bf16_f32 v10, v8, v9
	v_mov_b32_e32 v8, s9
	v_cndmask_b32_e64 v8, v4, v8, s[36:37]
	v_cndmask_b32_e64 v11, v11, 0, s[34:35]
	v_cndmask_b32_e64 v4, v8, v4, s[24:25]
	v_cndmask_b32_e64 v5, 0, v5, s[24:25]
	v_cndmask_b32_e64 v6, v6, 0, s[38:39]
	v_cndmask_b32_e64 v7, v7, 0, s[40:41]
	v_cvt_pk_bf16_f32 v11, v12, v11
	v_cvt_pk_bf16_f32 v4, v4, v5
	v_cvt_pk_bf16_f32 v5, v6, v7
	ds_write2_b64 v96, v[10:11], v[4:5] offset1:4
	s_waitcnt lgkmcnt(4)
	v_mfma_f32_16x16x32_bf16 v[8:11], v[192:195], v[228:231], 0
	v_mfma_f32_16x16x32_bf16 v[4:7], v[196:199], v[228:231], 0
	v_mfma_f32_16x16x32_bf16 v[8:11], v[200:203], v[232:235], v[8:11]
	v_mfma_f32_16x16x32_bf16 v[4:7], v[206:209], v[232:235], v[4:7]
	s_nop 7
	v_mov_b32_e32 v12, s9
	s_nop 3
	v_cndmask_b32_e64 v12, v8, v12, s[28:29]
	v_cndmask_b32_e64 v8, v12, v8, s[20:21]
	v_cndmask_b32_e64 v9, 0, v9, s[20:21]
	v_cndmask_b32_e64 v12, v10, 0, s[30:31]
	v_cvt_pk_bf16_f32 v10, v8, v9
	v_mov_b32_e32 v8, s9
	v_cndmask_b32_e64 v8, v4, v8, s[36:37]
	v_cndmask_b32_e64 v11, v11, 0, s[34:35]
	v_cndmask_b32_e64 v4, v8, v4, s[24:25]
	v_cndmask_b32_e64 v5, 0, v5, s[24:25]
	v_cndmask_b32_e64 v6, v6, 0, s[38:39]
	v_cndmask_b32_e64 v7, v7, 0, s[40:41]
	v_cvt_pk_bf16_f32 v11, v12, v11
	v_cvt_pk_bf16_f32 v4, v4, v5
	v_cvt_pk_bf16_f32 v5, v6, v7
	ds_write2_b64 v97, v[10:11], v[4:5] offset1:4
	s_waitcnt lgkmcnt(0)
	s_barrier
	ds_read_b128 v[4:7], v91 offset:55296
	ds_read_b128 v[8:11], v161 offset:64512
	ds_read_b128 v[12:15], v139 offset:64512
	s_waitcnt lgkmcnt(1)
	v_mfma_f32_16x16x32_bf16 v[8:11], v[8:11], v[4:7], 0
	s_waitcnt lgkmcnt(0)
	v_mfma_f32_16x16x32_bf16 v[4:7], v[12:15], v[4:7], 0
	ds_read_b128 v[12:15], v91 offset:55360
	ds_read_b128 v[16:19], v161 offset:64576
	s_waitcnt lgkmcnt(0)
	v_mfma_f32_16x16x32_bf16 v[8:11], v[16:19], v[12:15], v[8:11]
	ds_read_b128 v[16:19], v139 offset:64576
	s_waitcnt lgkmcnt(0)
	v_mfma_f32_16x16x32_bf16 v[4:7], v[16:19], v[12:15], v[4:7]
	s_nop 4
	v_cvt_pk_bf16_f32 v8, v8, v9
	v_cvt_pk_bf16_f32 v9, v10, v11
	s_nop 0
	v_cvt_pk_bf16_f32 v4, v4, v5
	v_cvt_pk_bf16_f32 v5, v6, v7
	ds_write2_b64 v140, v[8:9], v[4:5] offset1:4
	s_and_saveexec_b64 s[100:101], s[98:99]
	ds_write2_b64 v212, v[214:215], v[214:215] offset1:1
	s_mov_b64 exec, s[100:101]
	s_mov_b64 s[12:13], exec
	v_readlane_b32 s14, v244, 49
	v_readlane_b32 s15, v244, 50
	s_and_b64 s[14:15], s[12:13], s[14:15]
	s_mov_b64 exec, s[14:15]
	s_cbranch_execz .LBB0_935
; #define LAS __attribute__((address_space(3)))
; __device__ __forceinline__ unsigned pk2(float lo, float hi) { const f32x2c v = {lo, hi}; const bf16x2c b = __builtin_convertvector(v, bf16x2c); return __builtin_bit_cast(unsigned, b); }
; __device__ __forceinline__ void chunk_pre(const Params& p, LAS unsigned char* lds, int item, int next_item, int tid, int wave, int lane, h16 (&raw)[48]) {
;     ...
;     if (tid < 64) {
;         const int r = tid >> 4, j = tid & 15; float x[16];
; #pragma unroll
;         for (int i = 0; i < 16; ++i) x[i] = 0.f;
; #pragma unroll
;         for (int i = 0; i < 16; ++i) {
;             const LAS float* mrow = Mab + (16 * r + i) * 64 + 16 * r;
;             float v = (i == j) ? 1.f : 0.f;
; #pragma unroll
;             for (int q = 0; q < (i + 3) / 4; ++q) { const f32x4 m4 = *(const LAS f32x4*)(mrow + 4 * q);
;                 v += (m4.x * x[4 * q] + m4.y * x[4 * q + 1]) + (m4.z * x[4 * q + 2] + m4.w * x[4 * q + 3]); }
;             x[i] = v; TD[r * 256 + i * 16 + j] = v; Tb[(16 * r + i) * MS + 16 * r + j] = (bf16_t)(pk2(v, 0.f) & 0xffffu);
;         }
;     }
	v_mbcnt_lo_u32_b32 v203, -1, 0
	v_mbcnt_hi_u32_b32 v203, -1, v203
	v_lshrrev_b32_e32 v20, 4, v203
	v_and_b32_e32 v202, 15, v203
	v_lshlrev_b32_e32 v200, 8, v203
	v_lshl_add_u32 v200, v20, 6, v200
	v_add_u32_e32 v200, 0x16800, v200
	ds_read_b128 v[184:187], v200 offset:0
	ds_read_b128 v[188:191], v200 offset:16
	ds_read_b128 v[192:195], v200 offset:32
	ds_read_b128 v[196:199], v200 offset:48
	v_lshlrev_b32_e32 v201, 2, v202
	v_lshl_add_u32 v201, v20, 10, v201
	v_add_u32_e32 v201, 0x1f000, v201
	v_lshlrev_b32_e32 v202, 1, v202
	v_mov_b32_e32 v203, 0x920
	v_mad_u32_u24 v202, v20, v203, v202
	v_mov_b32_e32 v4, v101
	v_mov_b32_e32 v5, v103
	v_mov_b32_e32 v6, v104
	v_mov_b32_e32 v7, v105
	v_mov_b32_e32 v8, v106
	v_mov_b32_e32 v9, v107
	v_mov_b32_e32 v10, v108
	v_mov_b32_e32 v11, v109
	v_mov_b32_e32 v12, v110
	v_mov_b32_e32 v13, v111
	v_mov_b32_e32 v14, v112
	v_mov_b32_e32 v15, v113
	v_mov_b32_e32 v16, v114
	v_mov_b32_e32 v17, v115
	v_mov_b32_e32 v18, v116
	v_mov_b32_e32 v19, v117
	s_waitcnt lgkmcnt(0)
	v_fmac_f32_dpp v5, v184, v4 row_newbcast:1 row_mask:0xf bank_mask:0xf
	v_fmac_f32_dpp v6, v184, v4 row_newbcast:2 row_mask:0xf bank_mask:0xf
	v_fmac_f32_dpp v7, v184, v4 row_newbcast:3 row_mask:0xf bank_mask:0xf
	v_fmac_f32_dpp v8, v184, v4 row_newbcast:4 row_mask:0xf bank_mask:0xf
	v_fmac_f32_dpp v9, v184, v4 row_newbcast:5 row_mask:0xf bank_mask:0xf
	v_fmac_f32_dpp v10, v184, v4 row_newbcast:6 row_mask:0xf bank_mask:0xf
	v_fmac_f32_dpp v11, v184, v4 row_newbcast:7 row_mask:0xf bank_mask:0xf
	v_fmac_f32_dpp v12, v184, v4 row_newbcast:8 row_mask:0xf bank_mask:0xf
	v_fmac_f32_dpp v13, v184, v4 row_newbcast:9 row_mask:0xf bank_mask:0xf
	v_fmac_f32_dpp v14, v184, v4 row_newbcast:10 row_mask:0xf bank_mask:0xf
	v_fmac_f32_dpp v15, v184, v4 row_newbcast:11 row_mask:0xf bank_mask:0xf
	v_fmac_f32_dpp v16, v184, v4 row_newbcast:12 row_mask:0xf bank_mask:0xf
	v_fmac_f32_dpp v17, v184, v4 row_newbcast:13 row_mask:0xf bank_mask:0xf
	v_fmac_f32_dpp v18, v184, v4 row_newbcast:14 row_mask:0xf bank_mask:0xf
	v_fmac_f32_dpp v19, v184, v4 row_newbcast:15 row_mask:0xf bank_mask:0xf
	v_fmac_f32_dpp v6, v185, v5 row_newbcast:2 row_mask:0xf bank_mask:0xf
	v_fmac_f32_dpp v7, v185, v5 row_newbcast:3 row_mask:0xf bank_mask:0xf
	v_fmac_f32_dpp v8, v185, v5 row_newbcast:4 row_mask:0xf bank_mask:0xf
	v_fmac_f32_dpp v9, v185, v5 row_newbcast:5 row_mask:0xf bank_mask:0xf
	v_fmac_f32_dpp v10, v185, v5 row_newbcast:6 row_mask:0xf bank_mask:0xf
	v_fmac_f32_dpp v11, v185, v5 row_newbcast:7 row_mask:0xf bank_mask:0xf
	v_fmac_f32_dpp v12, v185, v5 row_newbcast:8 row_mask:0xf bank_mask:0xf
	v_fmac_f32_dpp v13, v185, v5 row_newbcast:9 row_mask:0xf bank_mask:0xf
	v_fmac_f32_dpp v14, v185, v5 row_newbcast:10 row_mask:0xf bank_mask:0xf
	v_fmac_f32_dpp v15, v185, v5 row_newbcast:11 row_mask:0xf bank_mask:0xf
	v_fmac_f32_dpp v16, v185, v5 row_newbcast:12 row_mask:0xf bank_mask:0xf
	v_fmac_f32_dpp v17, v185, v5 row_newbcast:13 row_mask:0xf bank_mask:0xf
	v_fmac_f32_dpp v18, v185, v5 row_newbcast:14 row_mask:0xf bank_mask:0xf
	v_fmac_f32_dpp v19, v185, v5 row_newbcast:15 row_mask:0xf bank_mask:0xf
	v_fmac_f32_dpp v7, v186, v6 row_newbcast:3 row_mask:0xf bank_mask:0xf
	v_fmac_f32_dpp v8, v186, v6 row_newbcast:4 row_mask:0xf bank_mask:0xf
	v_fmac_f32_dpp v9, v186, v6 row_newbcast:5 row_mask:0xf bank_mask:0xf
	v_fmac_f32_dpp v10, v186, v6 row_newbcast:6 row_mask:0xf bank_mask:0xf
	v_fmac_f32_dpp v11, v186, v6 row_newbcast:7 row_mask:0xf bank_mask:0xf
	v_fmac_f32_dpp v12, v186, v6 row_newbcast:8 row_mask:0xf bank_mask:0xf
	v_fmac_f32_dpp v13, v186, v6 row_newbcast:9 row_mask:0xf bank_mask:0xf
	v_fmac_f32_dpp v14, v186, v6 row_newbcast:10 row_mask:0xf bank_mask:0xf
	v_fmac_f32_dpp v15, v186, v6 row_newbcast:11 row_mask:0xf bank_mask:0xf
	v_fmac_f32_dpp v16, v186, v6 row_newbcast:12 row_mask:0xf bank_mask:0xf
	v_fmac_f32_dpp v17, v186, v6 row_newbcast:13 row_mask:0xf bank_mask:0xf
	v_fmac_f32_dpp v18, v186, v6 row_newbcast:14 row_mask:0xf bank_mask:0xf
	v_fmac_f32_dpp v19, v186, v6 row_newbcast:15 row_mask:0xf bank_mask:0xf
	v_fmac_f32_dpp v8, v187, v7 row_newbcast:4 row_mask:0xf bank_mask:0xf
	v_fmac_f32_dpp v9, v187, v7 row_newbcast:5 row_mask:0xf bank_mask:0xf
	v_fmac_f32_dpp v10, v187, v7 row_newbcast:6 row_mask:0xf bank_mask:0xf
	v_fmac_f32_dpp v11, v187, v7 row_newbcast:7 row_mask:0xf bank_mask:0xf
	v_fmac_f32_dpp v12, v187, v7 row_newbcast:8 row_mask:0xf bank_mask:0xf
	v_fmac_f32_dpp v13, v187, v7 row_newbcast:9 row_mask:0xf bank_mask:0xf
	v_fmac_f32_dpp v14, v187, v7 row_newbcast:10 row_mask:0xf bank_mask:0xf
	v_fmac_f32_dpp v15, v187, v7 row_newbcast:11 row_mask:0xf bank_mask:0xf
	v_fmac_f32_dpp v16, v187, v7 row_newbcast:12 row_mask:0xf bank_mask:0xf
	v_fmac_f32_dpp v17, v187, v7 row_newbcast:13 row_mask:0xf bank_mask:0xf
	v_fmac_f32_dpp v18, v187, v7 row_newbcast:14 row_mask:0xf bank_mask:0xf
	v_fmac_f32_dpp v19, v187, v7 row_newbcast:15 row_mask:0xf bank_mask:0xf
	v_fmac_f32_dpp v9, v188, v8 row_newbcast:5 row_mask:0xf bank_mask:0xf
	v_fmac_f32_dpp v10, v188, v8 row_newbcast:6 row_mask:0xf bank_mask:0xf
	v_fmac_f32_dpp v11, v188, v8 row_newbcast:7 row_mask:0xf bank_mask:0xf
	v_fmac_f32_dpp v12, v188, v8 row_newbcast:8 row_mask:0xf bank_mask:0xf
	v_fmac_f32_dpp v13, v188, v8 row_newbcast:9 row_mask:0xf bank_mask:0xf
	v_fmac_f32_dpp v14, v188, v8 row_newbcast:10 row_mask:0xf bank_mask:0xf
	v_fmac_f32_dpp v15, v188, v8 row_newbcast:11 row_mask:0xf bank_mask:0xf
	v_fmac_f32_dpp v16, v188, v8 row_newbcast:12 row_mask:0xf bank_mask:0xf
	v_fmac_f32_dpp v17, v188, v8 row_newbcast:13 row_mask:0xf bank_mask:0xf
	v_fmac_f32_dpp v18, v188, v8 row_newbcast:14 row_mask:0xf bank_mask:0xf
; #define LAS __attribute__((address_space(3)))
; __device__ __forceinline__ unsigned pk2(float lo, float hi) { const f32x2c v = {lo, hi}; const bf16x2c b = __builtin_convertvector(v, bf16x2c); return __builtin_bit_cast(unsigned, b); }
; __device__ __forceinline__ void chunk_pre(const Params& p, LAS unsigned char* lds, int item, int next_item, int tid, int wave, int lane, h16 (&raw)[48]) {
;     ...
;     if (tid < 64) {
;         const int r = tid >> 4, j = tid & 15; float x[16];
; #pragma unroll
;         for (int i = 0; i < 16; ++i) x[i] = 0.f;
; #pragma unroll
;         for (int i = 0; i < 16; ++i) {
;             const LAS float* mrow = Mab + (16 * r + i) * 64 + 16 * r;
;             float v = (i == j) ? 1.f : 0.f;
; #pragma unroll
;             for (int q = 0; q < (i + 3) / 4; ++q) { const f32x4 m4 = *(const LAS f32x4*)(mrow + 4 * q);
;                 v += (m4.x * x[4 * q] + m4.y * x[4 * q + 1]) + (m4.z * x[4 * q + 2] + m4.w * x[4 * q + 3]); }
;             x[i] = v; TD[r * 256 + i * 16 + j] = v; Tb[(16 * r + i) * MS + 16 * r + j] = (bf16_t)(pk2(v, 0.f) & 0xffffu);
;         }
;     }
	v_fmac_f32_dpp v19, v188, v8 row_newbcast:15 row_mask:0xf bank_mask:0xf
	v_fmac_f32_dpp v10, v189, v9 row_newbcast:6 row_mask:0xf bank_mask:0xf
	v_fmac_f32_dpp v11, v189, v9 row_newbcast:7 row_mask:0xf bank_mask:0xf
	v_fmac_f32_dpp v12, v189, v9 row_newbcast:8 row_mask:0xf bank_mask:0xf
	v_fmac_f32_dpp v13, v189, v9 row_newbcast:9 row_mask:0xf bank_mask:0xf
	v_fmac_f32_dpp v14, v189, v9 row_newbcast:10 row_mask:0xf bank_mask:0xf
	v_fmac_f32_dpp v15, v189, v9 row_newbcast:11 row_mask:0xf bank_mask:0xf
	v_fmac_f32_dpp v16, v189, v9 row_newbcast:12 row_mask:0xf bank_mask:0xf
	v_fmac_f32_dpp v17, v189, v9 row_newbcast:13 row_mask:0xf bank_mask:0xf
	v_fmac_f32_dpp v18, v189, v9 row_newbcast:14 row_mask:0xf bank_mask:0xf
	v_fmac_f32_dpp v19, v189, v9 row_newbcast:15 row_mask:0xf bank_mask:0xf
	v_fmac_f32_dpp v11, v190, v10 row_newbcast:7 row_mask:0xf bank_mask:0xf
	v_fmac_f32_dpp v12, v190, v10 row_newbcast:8 row_mask:0xf bank_mask:0xf
	v_fmac_f32_dpp v13, v190, v10 row_newbcast:9 row_mask:0xf bank_mask:0xf
	v_fmac_f32_dpp v14, v190, v10 row_newbcast:10 row_mask:0xf bank_mask:0xf
	v_fmac_f32_dpp v15, v190, v10 row_newbcast:11 row_mask:0xf bank_mask:0xf
	v_fmac_f32_dpp v16, v190, v10 row_newbcast:12 row_mask:0xf bank_mask:0xf
	v_fmac_f32_dpp v17, v190, v10 row_newbcast:13 row_mask:0xf bank_mask:0xf
	v_fmac_f32_dpp v18, v190, v10 row_newbcast:14 row_mask:0xf bank_mask:0xf
	v_fmac_f32_dpp v19, v190, v10 row_newbcast:15 row_mask:0xf bank_mask:0xf
	v_fmac_f32_dpp v12, v191, v11 row_newbcast:8 row_mask:0xf bank_mask:0xf
	v_fmac_f32_dpp v13, v191, v11 row_newbcast:9 row_mask:0xf bank_mask:0xf
	v_fmac_f32_dpp v14, v191, v11 row_newbcast:10 row_mask:0xf bank_mask:0xf
	v_fmac_f32_dpp v15, v191, v11 row_newbcast:11 row_mask:0xf bank_mask:0xf
	v_fmac_f32_dpp v16, v191, v11 row_newbcast:12 row_mask:0xf bank_mask:0xf
	v_fmac_f32_dpp v17, v191, v11 row_newbcast:13 row_mask:0xf bank_mask:0xf
	v_fmac_f32_dpp v18, v191, v11 row_newbcast:14 row_mask:0xf bank_mask:0xf
	v_fmac_f32_dpp v19, v191, v11 row_newbcast:15 row_mask:0xf bank_mask:0xf
	v_fmac_f32_dpp v13, v192, v12 row_newbcast:9 row_mask:0xf bank_mask:0xf
	v_fmac_f32_dpp v14, v192, v12 row_newbcast:10 row_mask:0xf bank_mask:0xf
	v_fmac_f32_dpp v15, v192, v12 row_newbcast:11 row_mask:0xf bank_mask:0xf
	v_fmac_f32_dpp v16, v192, v12 row_newbcast:12 row_mask:0xf bank_mask:0xf
	v_fmac_f32_dpp v17, v192, v12 row_newbcast:13 row_mask:0xf bank_mask:0xf
	v_fmac_f32_dpp v18, v192, v12 row_newbcast:14 row_mask:0xf bank_mask:0xf
	v_fmac_f32_dpp v19, v192, v12 row_newbcast:15 row_mask:0xf bank_mask:0xf
	v_fmac_f32_dpp v14, v193, v13 row_newbcast:10 row_mask:0xf bank_mask:0xf
	v_fmac_f32_dpp v15, v193, v13 row_newbcast:11 row_mask:0xf bank_mask:0xf
	v_fmac_f32_dpp v16, v193, v13 row_newbcast:12 row_mask:0xf bank_mask:0xf
	v_fmac_f32_dpp v17, v193, v13 row_newbcast:13 row_mask:0xf bank_mask:0xf
	v_fmac_f32_dpp v18, v193, v13 row_newbcast:14 row_mask:0xf bank_mask:0xf
	v_fmac_f32_dpp v19, v193, v13 row_newbcast:15 row_mask:0xf bank_mask:0xf
	v_fmac_f32_dpp v15, v194, v14 row_newbcast:11 row_mask:0xf bank_mask:0xf
	v_fmac_f32_dpp v16, v194, v14 row_newbcast:12 row_mask:0xf bank_mask:0xf
	v_fmac_f32_dpp v17, v194, v14 row_newbcast:13 row_mask:0xf bank_mask:0xf
	v_fmac_f32_dpp v18, v194, v14 row_newbcast:14 row_mask:0xf bank_mask:0xf
	v_fmac_f32_dpp v19, v194, v14 row_newbcast:15 row_mask:0xf bank_mask:0xf
	v_fmac_f32_dpp v16, v195, v15 row_newbcast:12 row_mask:0xf bank_mask:0xf
	v_fmac_f32_dpp v17, v195, v15 row_newbcast:13 row_mask:0xf bank_mask:0xf
	v_fmac_f32_dpp v18, v195, v15 row_newbcast:14 row_mask:0xf bank_mask:0xf
	v_fmac_f32_dpp v19, v195, v15 row_newbcast:15 row_mask:0xf bank_mask:0xf
	s_nop 1
	v_fmac_f32_dpp v17, v196, v16 row_newbcast:13 row_mask:0xf bank_mask:0xf
	v_fmac_f32_dpp v18, v196, v16 row_newbcast:14 row_mask:0xf bank_mask:0xf
	v_fmac_f32_dpp v19, v196, v16 row_newbcast:15 row_mask:0xf bank_mask:0xf
	s_nop 1
	v_fmac_f32_dpp v18, v197, v17 row_newbcast:14 row_mask:0xf bank_mask:0xf
	v_fmac_f32_dpp v19, v197, v17 row_newbcast:15 row_mask:0xf bank_mask:0xf
	s_nop 1
	v_fmac_f32_dpp v19, v198, v18 row_newbcast:15 row_mask:0xf bank_mask:0xf
	ds_write_b32 v201, v4 offset:0
	v_cvt_pk_bf16_f32 v20, v4, v4
	ds_write_b16 v202, v20 offset:0
	ds_write_b32 v201, v5 offset:64
	v_cvt_pk_bf16_f32 v20, v5, v5
	ds_write_b16 v202, v20 offset:144
	ds_write_b32 v201, v6 offset:128
	v_cvt_pk_bf16_f32 v20, v6, v6
	ds_write_b16 v202, v20 offset:288
	ds_write_b32 v201, v7 offset:192
	v_cvt_pk_bf16_f32 v20, v7, v7
	ds_write_b16 v202, v20 offset:432
	ds_write_b32 v201, v8 offset:256
	v_cvt_pk_bf16_f32 v20, v8, v8
	ds_write_b16 v202, v20 offset:576
	ds_write_b32 v201, v9 offset:320
	v_cvt_pk_bf16_f32 v20, v9, v9
	ds_write_b16 v202, v20 offset:720
	ds_write_b32 v201, v10 offset:384
	v_cvt_pk_bf16_f32 v20, v10, v10
	ds_write_b16 v202, v20 offset:864
	ds_write_b32 v201, v11 offset:448
	v_cvt_pk_bf16_f32 v20, v11, v11
	ds_write_b16 v202, v20 offset:1008
	ds_write_b32 v201, v12 offset:512
	v_cvt_pk_bf16_f32 v20, v12, v12
	ds_write_b16 v202, v20 offset:1152
	ds_write_b32 v201, v13 offset:576
	v_cvt_pk_bf16_f32 v20, v13, v13
	ds_write_b16 v202, v20 offset:1296
	ds_write_b32 v201, v14 offset:640
	v_cvt_pk_bf16_f32 v20, v14, v14
	ds_write_b16 v202, v20 offset:1440
	ds_write_b32 v201, v15 offset:704
	v_cvt_pk_bf16_f32 v20, v15, v15
	ds_write_b16 v202, v20 offset:1584
	ds_write_b32 v201, v16 offset:768
	v_cvt_pk_bf16_f32 v20, v16, v16
	ds_write_b16 v202, v20 offset:1728
	ds_write_b32 v201, v17 offset:832
	v_cvt_pk_bf16_f32 v20, v17, v17
	ds_write_b16 v202, v20 offset:1872
	ds_write_b32 v201, v18 offset:896
	v_cvt_pk_bf16_f32 v20, v18, v18
	ds_write_b16 v202, v20 offset:2016
	ds_write_b32 v201, v19 offset:960
	v_cvt_pk_bf16_f32 v20, v19, v19
	ds_write_b16 v202, v20 offset:2160
